# attention epilogue: sub-layer-norm weight loads issued 8 ahead with counted vmcnt instead of a vmcnt(0) after every 8-byte store
# speedup vs baseline: 1.0113x; 1.0075x over previous
; DI void attn_mfma_phase(PP P, int l, unsigned char* lds, int G, int cid) {
;     ...
;         if (map == 0) {
;             float ssq = 0.f;
; #pragma unroll
;             for (int et = 0; et < 4; ++et)
; #pragma unroll
;                 for (int k = 0; k < 16; ++k) { const float v = o[et][k] * inv - lam * OX[(qg * 64 + et * 16 + k) * 64 + lane]; o[et][k] = v; ssq += v * v; }
;             ssq += __shfl_xor(ssq, 32);
;             const float rs = rsqrtf(ssq * (1.f / 128.f) + 1e-5f) * (1.f - linit);
;             bf16_t* op = YY + ((size_t)b * SEQ + qpos) * 2048 + 1024 + h * 128 + 4 * hi;
;             const float* sw = P->in[19] + l * 128 + 4 * hi;
.LBB0_225:
	s_andn2_b64 vcc, exec, s[50:51]
	s_waitcnt lgkmcnt(0)
	s_barrier
	s_cbranch_vccnz .LBB0_208
	ds_read2st64_b32 v[12:13], v227 offset1:1
	ds_read2st64_b32 v[14:15], v227 offset0:2 offset1:3
	ds_read2st64_b32 v[82:83], v227 offset0:4 offset1:5
	ds_read2st64_b32 v[88:89], v227 offset0:6 offset1:7
	ds_read2st64_b32 v[92:93], v227 offset0:8 offset1:9
	ds_read2st64_b32 v[94:95], v227 offset0:10 offset1:11
	ds_read2st64_b32 v[96:97], v227 offset0:12 offset1:13
	ds_read2st64_b32 v[98:99], v227 offset0:14 offset1:15
	ds_read2st64_b32 v[100:101], v227 offset0:16 offset1:17
	ds_read2st64_b32 v[102:103], v227 offset0:18 offset1:19
	ds_read2st64_b32 v[104:105], v227 offset0:20 offset1:21
	ds_read2st64_b32 v[106:107], v227 offset0:22 offset1:23
	ds_read2st64_b32 v[108:109], v227 offset0:24 offset1:25
	ds_read2st64_b32 v[110:111], v227 offset0:26 offset1:27
	ds_read2st64_b32 v[144:145], v227 offset0:28 offset1:29
	ds_read2st64_b32 v[146:147], v227 offset0:30 offset1:31
	ds_read2st64_b32 v[148:149], v227 offset0:32 offset1:33
	ds_read2st64_b32 v[150:151], v227 offset0:34 offset1:35
	ds_read2st64_b32 v[152:153], v227 offset0:36 offset1:37
	ds_read2st64_b32 v[154:155], v227 offset0:38 offset1:39
	ds_read2st64_b32 v[156:157], v227 offset0:40 offset1:41
	ds_read2st64_b32 v[158:159], v227 offset0:42 offset1:43
	ds_read2st64_b32 v[168:169], v227 offset0:44 offset1:45
	ds_read2st64_b32 v[194:195], v227 offset0:46 offset1:47
	ds_read2st64_b32 v[196:197], v227 offset0:48 offset1:49
	ds_read2st64_b32 v[198:199], v227 offset0:50 offset1:51
	ds_read2st64_b32 v[230:231], v227 offset0:52 offset1:53
	ds_read2st64_b32 v[232:233], v227 offset0:54 offset1:55
	ds_read2st64_b32 v[90:91], v227 offset0:56 offset1:57
	ds_read2st64_b32 v[2:3], v227 offset0:60 offset1:61
	ds_read_b32 v4, v227 offset:15872
	ds_read2st64_b32 v[234:235], v227 offset0:58 offset1:59
	s_waitcnt lgkmcnt(14)
	v_pk_mul_f32 v[12:13], v[160:161], v[12:13]
	v_pk_mul_f32 v[14:15], v[160:161], v[14:15]
	v_pk_fma_f32 v[84:85], v[64:65], v[0:1], v[12:13] op_sel_hi:[1,0,1] neg_lo:[0,0,1] neg_hi:[0,0,1]
	v_pk_mul_f32 v[12:13], v[160:161], v[88:89]
	v_pk_fma_f32 v[80:81], v[66:67], v[0:1], v[14:15] op_sel_hi:[1,0,1] neg_lo:[0,0,1] neg_hi:[0,0,1]
	v_pk_fma_f32 v[64:65], v[70:71], v[0:1], v[12:13] op_sel_hi:[1,0,1] neg_lo:[0,0,1] neg_hi:[0,0,1]
	v_pk_mul_f32 v[12:13], v[160:161], v[82:83]
	v_add_u32_e32 v5, s66, v219
	v_pk_fma_f32 v[82:83], v[68:69], v[0:1], v[12:13] op_sel_hi:[1,0,1] neg_lo:[0,0,1] neg_hi:[0,0,1]
	v_pk_mul_f32 v[12:13], v[160:161], v[94:95]
	ds_read_b32 v5, v5
	v_pk_fma_f32 v[66:67], v[74:75], v[0:1], v[12:13] op_sel_hi:[1,0,1] neg_lo:[0,0,1] neg_hi:[0,0,1]
	v_pk_mul_f32 v[12:13], v[160:161], v[92:93]
	s_waitcnt lgkmcnt(3)
	v_pk_mul_f32 v[2:3], v[160:161], v[2:3]
	v_pk_fma_f32 v[88:89], v[72:73], v[0:1], v[12:13] op_sel_hi:[1,0,1] neg_lo:[0,0,1] neg_hi:[0,0,1]
	v_pk_mul_f32 v[12:13], v[160:161], v[98:99]
	v_pk_fma_f32 v[6:7], v[28:29], v[0:1], v[2:3] op_sel_hi:[1,0,1] neg_lo:[0,0,1] neg_hi:[0,0,1]
	v_pk_fma_f32 v[68:69], v[78:79], v[0:1], v[12:13] op_sel_hi:[1,0,1] neg_lo:[0,0,1] neg_hi:[0,0,1]
	v_pk_mul_f32 v[12:13], v[160:161], v[96:97]
	s_waitcnt lgkmcnt(0)
	v_pk_mul_f32 v[2:3], v[160:161], v[4:5]
	v_pk_fma_f32 v[76:77], v[76:77], v[0:1], v[12:13] op_sel_hi:[1,0,1] neg_lo:[0,0,1] neg_hi:[0,0,1]
	v_pk_mul_f32 v[12:13], v[160:161], v[102:103]
	s_load_dwordx2 s[4:5], s[0:1], 0x98
	v_pk_fma_f32 v[70:71], v[50:51], v[0:1], v[12:13] op_sel_hi:[1,0,1] neg_lo:[0,0,1] neg_hi:[0,0,1]
	v_pk_mul_f32 v[12:13], v[160:161], v[100:101]
	v_pk_fma_f32 v[8:9], v[30:31], v[0:1], v[2:3] op_sel_hi:[1,0,1] neg_lo:[0,0,1] neg_hi:[0,0,1]
	v_pk_fma_f32 v[72:73], v[48:49], v[0:1], v[12:13] op_sel_hi:[1,0,1] neg_lo:[0,0,1] neg_hi:[0,0,1]
	v_pk_mul_f32 v[12:13], v[160:161], v[106:107]
	s_lshl_b32 s20, s83, 1
	v_pk_fma_f32 v[48:49], v[54:55], v[0:1], v[12:13] op_sel_hi:[1,0,1] neg_lo:[0,0,1] neg_hi:[0,0,1]
	v_pk_mul_f32 v[12:13], v[160:161], v[104:105]
	s_waitcnt lgkmcnt(0)
	s_add_u32 s12, s4, s58
	v_pk_fma_f32 v[74:75], v[52:53], v[0:1], v[12:13] op_sel_hi:[1,0,1] neg_lo:[0,0,1] neg_hi:[0,0,1]
	v_pk_mul_f32 v[12:13], v[160:161], v[110:111]
	v_pk_mul_f32 v[14:15], v[160:161], v[230:231]
	v_pk_fma_f32 v[50:51], v[58:59], v[0:1], v[12:13] op_sel_hi:[1,0,1] neg_lo:[0,0,1] neg_hi:[0,0,1]
	v_pk_mul_f32 v[12:13], v[160:161], v[108:109]
	s_addc_u32 s13, s5, s59
	v_pk_fma_f32 v[56:57], v[56:57], v[0:1], v[12:13] op_sel_hi:[1,0,1] neg_lo:[0,0,1] neg_hi:[0,0,1]
	v_pk_mul_f32 v[12:13], v[160:161], v[146:147]
	v_lshlrev_b32_e32 v189, 2, v170
	v_pk_fma_f32 v[52:53], v[62:63], v[0:1], v[12:13] op_sel_hi:[1,0,1] neg_lo:[0,0,1] neg_hi:[0,0,1]
	v_pk_mul_f32 v[12:13], v[160:161], v[144:145]
	v_pk_mul_f32 v[238:239], v[84:85], v[84:85]
	v_pk_fma_f32 v[58:59], v[60:61], v[0:1], v[12:13] op_sel_hi:[1,0,1] neg_lo:[0,0,1] neg_hi:[0,0,1]
	v_pk_mul_f32 v[12:13], v[160:161], v[150:151]
	v_pk_fma_f32 v[20:21], v[20:21], v[0:1], v[14:15] op_sel_hi:[1,0,1] neg_lo:[0,0,1] neg_hi:[0,0,1]
	v_pk_fma_f32 v[34:35], v[34:35], v[0:1], v[12:13] op_sel_hi:[1,0,1] neg_lo:[0,0,1] neg_hi:[0,0,1]
	v_pk_mul_f32 v[12:13], v[160:161], v[148:149]
	v_pk_mul_f32 v[14:15], v[160:161], v[234:235]
	v_pk_fma_f32 v[54:55], v[32:33], v[0:1], v[12:13] op_sel_hi:[1,0,1] neg_lo:[0,0,1] neg_hi:[0,0,1]
	v_pk_mul_f32 v[12:13], v[160:161], v[154:155]
	global_load_dwordx4 v[112:115], v189, s[12:13]
	global_load_dwordx4 v[116:119], v189, s[12:13] offset:32
	global_load_dwordx4 v[120:123], v189, s[12:13] offset:64
	global_load_dwordx4 v[124:127], v189, s[12:13] offset:96
	global_load_dwordx4 v[128:131], v189, s[12:13] offset:128
	global_load_dwordx4 v[132:135], v189, s[12:13] offset:160
; DI void attn_mfma_phase(PP P, int l, unsigned char* lds, int G, int cid) {
;     ...
;             float ssq = 0.f;
; #pragma unroll
;             for (int et = 0; et < 4; ++et)
; #pragma unroll
;                 for (int k = 0; k < 16; ++k) { const float v = o[et][k] * inv - lam * OX[(qg * 64 + et * 16 + k) * 64 + lane]; o[et][k] = v; ssq += v * v; }
;             ssq += __shfl_xor(ssq, 32);
;             const float rs = rsqrtf(ssq * (1.f / 128.f) + 1e-5f) * (1.f - linit);
;             bf16_t* op = YY + ((size_t)b * SEQ + qpos) * 2048 + 1024 + h * 128 + 4 * hi;
;             const float* sw = P->in[19] + l * 128 + 4 * hi;
	global_load_dwordx4 v[136:139], v189, s[12:13] offset:192
	global_load_dwordx4 v[140:143], v189, s[12:13] offset:224
	v_pk_fma_f32 v[28:29], v[38:39], v[0:1], v[12:13] op_sel_hi:[1,0,1] neg_lo:[0,0,1] neg_hi:[0,0,1]
	v_pk_mul_f32 v[12:13], v[160:161], v[152:153]
	v_pk_mul_f32 v[236:237], v[80:81], v[80:81]
	v_pk_fma_f32 v[36:37], v[36:37], v[0:1], v[12:13] op_sel_hi:[1,0,1] neg_lo:[0,0,1] neg_hi:[0,0,1]
	v_pk_mul_f32 v[12:13], v[160:161], v[158:159]
	v_pk_fma_f32 v[14:15], v[26:27], v[0:1], v[14:15] op_sel_hi:[1,0,1] neg_lo:[0,0,1] neg_hi:[0,0,1]
	v_pk_fma_f32 v[30:31], v[42:43], v[0:1], v[12:13] op_sel_hi:[1,0,1] neg_lo:[0,0,1] neg_hi:[0,0,1]
	v_pk_mul_f32 v[12:13], v[160:161], v[156:157]
	v_pk_mul_f32 v[242:243], v[82:83], v[82:83]
	v_pk_fma_f32 v[38:39], v[40:41], v[0:1], v[12:13] op_sel_hi:[1,0,1] neg_lo:[0,0,1] neg_hi:[0,0,1]
	v_pk_mul_f32 v[12:13], v[160:161], v[194:195]
	v_pk_mul_f32 v[240:241], v[64:65], v[64:65]
	v_pk_fma_f32 v[32:33], v[46:47], v[0:1], v[12:13] op_sel_hi:[1,0,1] neg_lo:[0,0,1] neg_hi:[0,0,1]
	v_pk_mul_f32 v[12:13], v[160:161], v[168:169]
	v_pk_mul_f32 v[92:93], v[88:89], v[88:89]
	v_pk_fma_f32 v[40:41], v[44:45], v[0:1], v[12:13] op_sel_hi:[1,0,1] neg_lo:[0,0,1] neg_hi:[0,0,1]
	v_pk_mul_f32 v[12:13], v[160:161], v[198:199]
	v_pk_mul_f32 v[94:95], v[66:67], v[66:67]
	v_pk_fma_f32 v[18:19], v[18:19], v[0:1], v[12:13] op_sel_hi:[1,0,1] neg_lo:[0,0,1] neg_hi:[0,0,1]
	v_pk_mul_f32 v[12:13], v[160:161], v[196:197]
	v_pk_mul_f32 v[96:97], v[76:77], v[76:77]
	v_pk_fma_f32 v[16:17], v[16:17], v[0:1], v[12:13] op_sel_hi:[1,0,1] neg_lo:[0,0,1] neg_hi:[0,0,1]
	v_pk_mul_f32 v[12:13], v[160:161], v[232:233]
	v_pk_mul_f32 v[78:79], v[68:69], v[68:69]
	v_pk_fma_f32 v[12:13], v[22:23], v[0:1], v[12:13] op_sel_hi:[1,0,1] neg_lo:[0,0,1] neg_hi:[0,0,1]
	v_pk_mul_f32 v[22:23], v[160:161], v[90:91]
	v_pk_mul_f32 v[100:101], v[72:73], v[72:73]
	v_pk_fma_f32 v[22:23], v[24:25], v[0:1], v[22:23] op_sel_hi:[1,0,1] neg_lo:[0,0,1] neg_hi:[0,0,1]
	v_add_f32_e32 v0, v238, v239
	v_add_f32_e32 v0, v0, v236
	v_add_f32_e32 v0, v0, v237
	v_add_f32_e32 v0, v0, v242
	v_add_f32_e32 v0, v0, v243
	v_add_f32_e32 v0, v0, v240
	v_add_f32_e32 v0, v0, v241
	v_add_f32_e32 v0, v0, v92
	v_add_f32_e32 v0, v0, v93
	v_add_f32_e32 v0, v0, v94
	v_add_f32_e32 v0, v0, v95
	v_add_f32_e32 v0, v0, v96
	v_add_f32_e32 v0, v0, v97
	v_add_f32_e32 v0, v0, v78
	v_add_f32_e32 v0, v0, v79
	v_add_f32_e32 v0, v0, v100
	v_pk_mul_f32 v[98:99], v[70:71], v[70:71]
	v_add_f32_e32 v0, v0, v101
	v_add_f32_e32 v0, v0, v98
	v_pk_mul_f32 v[104:105], v[74:75], v[74:75]
	v_add_f32_e32 v0, v0, v99
	v_add_f32_e32 v0, v0, v104
	v_pk_mul_f32 v[102:103], v[48:49], v[48:49]
	v_add_f32_e32 v0, v0, v105
	v_add_f32_e32 v0, v0, v102
	v_pk_mul_f32 v[108:109], v[56:57], v[56:57]
	v_add_f32_e32 v0, v0, v103
	v_add_f32_e32 v0, v0, v108
	v_pk_mul_f32 v[106:107], v[50:51], v[50:51]
	v_add_f32_e32 v0, v0, v109
	v_add_f32_e32 v0, v0, v106
	v_pk_mul_f32 v[60:61], v[58:59], v[58:59]
	v_add_f32_e32 v0, v0, v107
	v_add_f32_e32 v0, v0, v60
	v_pk_mul_f32 v[62:63], v[52:53], v[52:53]
	v_add_f32_e32 v0, v0, v61
	v_add_f32_e32 v0, v0, v62
	v_pk_mul_f32 v[144:145], v[54:55], v[54:55]
	v_add_f32_e32 v0, v0, v63
	v_add_f32_e32 v0, v0, v144
	v_pk_mul_f32 v[110:111], v[34:35], v[34:35]
	v_add_f32_e32 v0, v0, v145
	v_add_f32_e32 v0, v0, v110
	v_pk_mul_f32 v[148:149], v[36:37], v[36:37]
	v_add_f32_e32 v0, v0, v111
	v_add_f32_e32 v0, v0, v148
	v_pk_mul_f32 v[146:147], v[28:29], v[28:29]
	v_add_f32_e32 v0, v0, v149
	v_add_f32_e32 v0, v0, v146
	v_pk_mul_f32 v[150:151], v[38:39], v[38:39]
	v_add_f32_e32 v0, v0, v147
	v_add_f32_e32 v0, v0, v150
	v_pk_mul_f32 v[42:43], v[30:31], v[30:31]
	v_add_f32_e32 v0, v0, v151
	v_add_f32_e32 v0, v0, v42
	v_pk_mul_f32 v[44:45], v[40:41], v[40:41]
	v_add_f32_e32 v0, v0, v43
	v_add_f32_e32 v0, v0, v44
	v_pk_mul_f32 v[46:47], v[32:33], v[32:33]
	v_add_f32_e32 v0, v0, v45
	v_add_f32_e32 v0, v0, v46
	v_pk_mul_f32 v[154:155], v[16:17], v[16:17]
	v_add_f32_e32 v0, v0, v47
	v_add_f32_e32 v0, v0, v154
	v_pk_mul_f32 v[152:153], v[18:19], v[18:19]
	v_add_f32_e32 v0, v0, v155
	v_add_f32_e32 v0, v0, v152
	v_pk_mul_f32 v[158:159], v[20:21], v[20:21]
	v_add_f32_e32 v0, v0, v153
	v_add_f32_e32 v0, v0, v158
	v_pk_mul_f32 v[156:157], v[12:13], v[12:13]
	v_add_f32_e32 v0, v0, v159
	v_add_f32_e32 v0, v0, v156
	v_pk_mul_f32 v[24:25], v[22:23], v[22:23]
	v_add_f32_e32 v0, v0, v157
	v_add_f32_e32 v0, v0, v24
	v_pk_mul_f32 v[26:27], v[14:15], v[14:15]
	v_add_f32_e32 v0, v0, v25
	v_add_f32_e32 v0, v0, v26
	v_pk_mul_f32 v[10:11], v[6:7], v[6:7]
	v_add_f32_e32 v0, v0, v27
	v_add_f32_e32 v0, v0, v10
	v_pk_mul_f32 v[86:87], v[8:9], v[8:9]
	v_add_f32_e32 v0, v0, v11
	v_add_f32_e32 v0, v0, v86
	v_add_f32_e32 v0, v0, v87
	ds_bpermute_b32 v24, v218, v0
	v_lshlrev_b64 v[10:11], 12, v[192:193]
	v_lshl_add_u64 v[10:11], s[70:71], 0, v[10:11]
	v_lshl_add_u64 v[10:11], v[10:11], 0, s[20:21]
	s_mov_b32 s4, 0x1d400000
	s_waitcnt lgkmcnt(0)
	v_add_f32_e32 v0, v0, v24
	v_mov_b32_e32 v24, 0x3727c5ac
	v_fmamk_f32 v0, v0, 0x3c000000, v24
	v_mul_f32_e32 v24, 0x4b800000, v0
	v_cmp_gt_f32_e32 vcc, s27, v0
	s_nop 1
	v_cndmask_b32_e32 v0, v0, v24, vcc
	v_rsq_f32_e32 v24, v0
	v_lshlrev_b32_e32 v0, 1, v170
	v_lshl_add_u64 v[10:11], v[10:11], 0, v[0:1]
	v_mul_f32_e32 v0, 0x45800000, v24
	v_cndmask_b32_e32 v0, v24, v0, vcc
	v_mul_f32_e32 v0, v220, v0
	v_pk_mul_f32 v[24:25], v[84:85], v[0:1] op_sel_hi:[1,0]
	v_pk_mul_f32 v[26:27], v[66:67], v[0:1] op_sel_hi:[1,0]
	s_waitcnt vmcnt(7)
; DI unsigned pk_bf16(float lo, float hi) { f32x2v v = {lo, hi}; bf16x2v b = __builtin_convertvector(v, bf16x2v); return __builtin_bit_cast(unsigned, b); }
; DI void attn_mfma_phase(PP P, int l, unsigned char* lds, int G, int cid) {
;     ...
;             bf16_t* op = YY + ((size_t)b * SEQ + qpos) * 2048 + 1024 + h * 128 + 4 * hi;
;             const float* sw = P->in[19] + l * 128 + 4 * hi;
; #pragma unroll
;             for (int et = 0; et < 4; ++et)
; #pragma unroll
;                 for (int g4 = 0; g4 < 4; ++g4) {
;                     const f32x4 wv = *(const f32x4*)(sw + et * 32 + 8 * g4);
;                     u32x2 wo; wo.x = pk_bf16(o[et][4 * g4] * rs * wv.x, o[et][4 * g4 + 1] * rs * wv.y); wo.y = pk_bf16(o[et][4 * g4 + 2] * rs * wv.z, o[et][4 * g4 + 3] * rs * wv.w);
;                     *(u32x2*)(op + et * 32 + 8 * g4) = wo;
;                 }
	v_pk_mul_f32 v[2:3], v[112:113], v[24:25]
	v_pk_mul_f32 v[24:25], v[80:81], v[0:1] op_sel_hi:[1,0]
	v_cvt_pk_bf16_f32 v2, v2, v3
	v_pk_mul_f32 v[4:5], v[114:115], v[24:25]
	v_pk_mul_f32 v[24:25], v[82:83], v[0:1] op_sel_hi:[1,0]
	v_cvt_pk_bf16_f32 v3, v4, v5
	v_add_co_u32_e32 v4, vcc, s4, v10
	s_mov_b64 s[4:5], 0x1d400800
	s_nop 0
	v_addc_co_u32_e32 v5, vcc, 0, v11, vcc
	global_store_dwordx2 v[4:5], v[2:3], off offset:2048
	global_load_dwordx4 v[112:115], v189, s[12:13] offset:256
	v_lshl_add_u64 v[10:11], v[10:11], 0, s[4:5]
	v_pk_mul_f32 v[16:17], v[16:17], v[0:1] op_sel_hi:[1,0]
	v_pk_mul_f32 v[18:19], v[18:19], v[0:1] op_sel_hi:[1,0]
	v_pk_mul_f32 v[12:13], v[12:13], v[0:1] op_sel_hi:[1,0]
	v_pk_mul_f32 v[14:15], v[14:15], v[0:1] op_sel_hi:[1,0]
	v_pk_mul_f32 v[6:7], v[6:7], v[0:1] op_sel_hi:[1,0]
	v_pk_mul_f32 v[8:9], v[8:9], v[0:1] op_sel_hi:[1,0]
	s_waitcnt vmcnt(8)
	v_pk_mul_f32 v[2:3], v[116:117], v[24:25]
	v_pk_mul_f32 v[24:25], v[64:65], v[0:1] op_sel_hi:[1,0]
	v_cvt_pk_bf16_f32 v2, v2, v3
	v_pk_mul_f32 v[4:5], v[118:119], v[24:25]
	v_pk_mul_f32 v[24:25], v[88:89], v[0:1] op_sel_hi:[1,0]
	v_cvt_pk_bf16_f32 v3, v4, v5
	global_store_dwordx2 v[10:11], v[2:3], off offset:16
	global_load_dwordx4 v[116:119], v189, s[12:13] offset:288
	s_waitcnt vmcnt(9)
	v_pk_mul_f32 v[2:3], v[120:121], v[24:25]
	v_pk_mul_f32 v[4:5], v[122:123], v[26:27]
	v_cvt_pk_bf16_f32 v2, v2, v3
	v_cvt_pk_bf16_f32 v3, v4, v5
	global_store_dwordx2 v[10:11], v[2:3], off offset:32
	global_load_dwordx4 v[120:123], v189, s[12:13] offset:320
	v_pk_mul_f32 v[24:25], v[76:77], v[0:1] op_sel_hi:[1,0]
	v_pk_mul_f32 v[26:27], v[68:69], v[0:1] op_sel_hi:[1,0]
	s_waitcnt vmcnt(10)
	v_pk_mul_f32 v[2:3], v[124:125], v[24:25]
	v_pk_mul_f32 v[4:5], v[126:127], v[26:27]
	v_cvt_pk_bf16_f32 v2, v2, v3
	v_cvt_pk_bf16_f32 v3, v4, v5
	global_store_dwordx2 v[10:11], v[2:3], off offset:48
	global_load_dwordx4 v[124:127], v189, s[12:13] offset:352
	v_pk_mul_f32 v[24:25], v[72:73], v[0:1] op_sel_hi:[1,0]
	v_pk_mul_f32 v[26:27], v[70:71], v[0:1] op_sel_hi:[1,0]
	s_waitcnt vmcnt(11)
	v_pk_mul_f32 v[2:3], v[128:129], v[24:25]
	v_pk_mul_f32 v[4:5], v[130:131], v[26:27]
	v_cvt_pk_bf16_f32 v2, v2, v3
	v_cvt_pk_bf16_f32 v3, v4, v5
	global_store_dwordx2 v[10:11], v[2:3], off offset:64
	global_load_dwordx4 v[128:131], v189, s[12:13] offset:384
	v_pk_mul_f32 v[24:25], v[74:75], v[0:1] op_sel_hi:[1,0]
	v_pk_mul_f32 v[26:27], v[48:49], v[0:1] op_sel_hi:[1,0]
	s_waitcnt vmcnt(12)
	v_pk_mul_f32 v[2:3], v[132:133], v[24:25]
	v_pk_mul_f32 v[4:5], v[134:135], v[26:27]
	v_cvt_pk_bf16_f32 v2, v2, v3
	v_cvt_pk_bf16_f32 v3, v4, v5
	global_store_dwordx2 v[10:11], v[2:3], off offset:80
	global_load_dwordx4 v[132:135], v189, s[12:13] offset:416
	v_pk_mul_f32 v[24:25], v[56:57], v[0:1] op_sel_hi:[1,0]
	v_pk_mul_f32 v[26:27], v[50:51], v[0:1] op_sel_hi:[1,0]
	s_waitcnt vmcnt(13)
	v_pk_mul_f32 v[2:3], v[24:25], v[136:137]
	v_pk_mul_f32 v[4:5], v[26:27], v[138:139]
	v_cvt_pk_bf16_f32 v2, v2, v3
	v_cvt_pk_bf16_f32 v3, v4, v5
	global_store_dwordx2 v[10:11], v[2:3], off offset:96
	global_load_dwordx4 v[136:139], v189, s[12:13] offset:448
	v_pk_mul_f32 v[24:25], v[58:59], v[0:1] op_sel_hi:[1,0]
	v_pk_mul_f32 v[26:27], v[52:53], v[0:1] op_sel_hi:[1,0]
	s_waitcnt vmcnt(14)
	v_pk_mul_f32 v[2:3], v[24:25], v[140:141]
	v_pk_mul_f32 v[4:5], v[26:27], v[142:143]
	v_cvt_pk_bf16_f32 v2, v2, v3
	v_cvt_pk_bf16_f32 v3, v4, v5
	global_store_dwordx2 v[10:11], v[2:3], off offset:112
	global_load_dwordx4 v[140:143], v189, s[12:13] offset:480
	v_pk_mul_f32 v[24:25], v[54:55], v[0:1] op_sel_hi:[1,0]
	v_pk_mul_f32 v[26:27], v[34:35], v[0:1] op_sel_hi:[1,0]
	s_waitcnt vmcnt(14)
	v_pk_mul_f32 v[2:3], v[24:25], v[112:113]
	v_pk_mul_f32 v[4:5], v[26:27], v[114:115]
	v_cvt_pk_bf16_f32 v2, v2, v3
	v_cvt_pk_bf16_f32 v3, v4, v5
	global_store_dwordx2 v[10:11], v[2:3], off offset:128
	v_pk_mul_f32 v[24:25], v[36:37], v[0:1] op_sel_hi:[1,0]
	v_pk_mul_f32 v[26:27], v[28:29], v[0:1] op_sel_hi:[1,0]
	s_waitcnt vmcnt(13)
	v_pk_mul_f32 v[2:3], v[24:25], v[116:117]
	v_pk_mul_f32 v[4:5], v[26:27], v[118:119]
	v_cvt_pk_bf16_f32 v2, v2, v3
	v_cvt_pk_bf16_f32 v3, v4, v5
	global_store_dwordx2 v[10:11], v[2:3], off offset:144
	v_pk_mul_f32 v[24:25], v[38:39], v[0:1] op_sel_hi:[1,0]
	v_pk_mul_f32 v[26:27], v[30:31], v[0:1] op_sel_hi:[1,0]
	s_waitcnt vmcnt(12)
	v_pk_mul_f32 v[2:3], v[24:25], v[120:121]
	v_pk_mul_f32 v[4:5], v[26:27], v[122:123]
	v_cvt_pk_bf16_f32 v2, v2, v3
	v_cvt_pk_bf16_f32 v3, v4, v5
	global_store_dwordx2 v[10:11], v[2:3], off offset:160
	v_pk_mul_f32 v[24:25], v[40:41], v[0:1] op_sel_hi:[1,0]
	v_pk_mul_f32 v[26:27], v[32:33], v[0:1] op_sel_hi:[1,0]
	s_waitcnt vmcnt(11)
	v_pk_mul_f32 v[2:3], v[24:25], v[124:125]
	v_pk_mul_f32 v[4:5], v[26:27], v[126:127]
	v_cvt_pk_bf16_f32 v2, v2, v3
	v_cvt_pk_bf16_f32 v3, v4, v5
	global_store_dwordx2 v[10:11], v[2:3], off offset:176
	s_waitcnt vmcnt(10)
	v_pk_mul_f32 v[2:3], v[16:17], v[128:129]
	v_pk_mul_f32 v[4:5], v[18:19], v[130:131]
	v_cvt_pk_bf16_f32 v2, v2, v3
	v_cvt_pk_bf16_f32 v3, v4, v5
	global_store_dwordx2 v[10:11], v[2:3], off offset:192
	v_pk_mul_f32 v[16:17], v[20:21], v[0:1] op_sel_hi:[1,0]
	s_waitcnt vmcnt(9)
	v_pk_mul_f32 v[4:5], v[12:13], v[134:135]
	v_pk_mul_f32 v[2:3], v[16:17], v[132:133]
	v_pk_mul_f32 v[12:13], v[22:23], v[0:1] op_sel_hi:[1,0]
	v_cvt_pk_bf16_f32 v2, v2, v3
	v_cvt_pk_bf16_f32 v3, v4, v5
	global_store_dwordx2 v[10:11], v[2:3], off offset:208
	s_waitcnt vmcnt(8)
	v_pk_mul_f32 v[2:3], v[12:13], v[136:137]
	v_pk_mul_f32 v[4:5], v[14:15], v[138:139]
	v_cvt_pk_bf16_f32 v2, v2, v3
	v_cvt_pk_bf16_f32 v3, v4, v5
	global_store_dwordx2 v[10:11], v[2:3], off offset:224
	s_waitcnt vmcnt(7)
	v_pk_mul_f32 v[2:3], v[6:7], v[140:141]
	v_pk_mul_f32 v[4:5], v[8:9], v[142:143]
	v_cvt_pk_bf16_f32 v2, v2, v3
	v_cvt_pk_bf16_f32 v3, v4, v5
	global_store_dwordx2 v[10:11], v[2:3], off offset:240
	s_branch .LBB0_208
